# v105 + grid barrier: followers spin on the top-level generation word (per-XCD word still bumped)
# baseline (speedup 1.0000x reference)
.LBB0_1502:
	s_or_b64 exec, exec, s[2:3]
	v_cvt_f32_u32_e32 v4, v2
	s_waitcnt vmcnt(0)
	v_readfirstlane_b32 s2, v3
	v_sub_u32_e32 v3, 0, v2
	v_rcp_iflag_f32_e32 v4, v4
	v_add_u32_e32 v5, s2, v1
	v_mul_f32_e32 v4, 0x4f7ffffe, v4
	v_cvt_u32_f32_e32 v4, v4
	v_mul_lo_u32 v1, v3, v4
	v_mul_hi_u32 v1, v4, v1
	v_add_u32_e32 v1, v4, v1
	v_mul_hi_u32 v1, v5, v1
	v_mul_lo_u32 v3, v1, v2
	v_sub_u32_e32 v3, v5, v3
	v_add_u32_e32 v4, 1, v1
	v_cmp_ge_u32_e32 vcc, v3, v2
	s_nop 1
	v_cndmask_b32_e32 v1, v1, v4, vcc
	v_sub_u32_e32 v4, v3, v2
	v_cndmask_b32_e32 v3, v3, v4, vcc
	v_add_u32_e32 v4, 1, v1
	v_cmp_ge_u32_e32 vcc, v3, v2
	v_add_u32_e32 v3, 1, v5
	s_nop 0
	v_cndmask_b32_e32 v1, v1, v4, vcc
	v_mul_lo_u32 v4, v2, v1
	v_add_u32_e32 v2, v4, v2
	v_cmp_ne_u32_e32 vcc, v3, v2
	s_and_saveexec_b64 s[2:3], vcc
	s_xor_b64 s[2:3], exec, s[2:3]
	s_cbranch_execz .LBB0_1516
	v_readlane_b32 s4, v251, 26
	v_readlane_b32 s5, v251, 27
	s_waitcnt lgkmcnt(0)
	s_nop 3
	global_load_dword v0, v31, s[4:5] sc1
	s_waitcnt vmcnt(0)
	v_cmp_eq_u32_e32 vcc, v0, v1
	s_and_saveexec_b64 s[4:5], vcc
	s_cbranch_execz .LBB0_1515
	s_mov_b32 s16, 1
	s_mov_b64 s[6:7], 0
	s_branch .LBB0_1506

.LBB0_1510:
	v_readlane_b32 s10, v251, 26
	v_readlane_b32 s11, v251, 27
	s_add_i32 s16, s16, 1
	s_mov_b64 s[12:13], -1
	s_nop 2
	global_load_dword v0, v31, s[10:11] sc1
	s_waitcnt vmcnt(0)
	v_cmp_ne_u32_e32 vcc, v0, v1
	s_orn2_b64 s[10:11], vcc, exec
	s_branch .LBB0_1505
